# G1/G4 main loop: all LDS-DMAs of a phase issued right after the fragment reads (early issue) instead of spread over MFMA groups; on top of gemm96 early issue
# baseline (speedup 1.0000x reference)
.LBB1_56:
	s_mul_i32 s15, s13, 0x4000
	s_add_i32 s15, s15, 16
	s_add_i32 s41, s13, 2
	s_cmp_ge_u32 s41, 3
	s_cselect_b32 s42, 3, 0
	s_sub_i32 s41, s41, s42
	s_mul_i32 s41, s41, 0x4000
	s_add_i32 s41, s41, 16
	s_add_i32 s41, s41, s54
	s_add_i32 s32, s14, 1
	s_min_u32 s32, s32, 15
	s_lshl_b32 s32, s32, 7
	s_add_u32 s50, s18, s32
	s_addc_u32 s51, s19, 0
	s_waitcnt vmcnt(4)
	s_barrier
	v_add_u32_e32 v202, s15, v196
	v_add_u32_e32 v203, s15, v197
	ds_read_b128 v[140:143], v198 offset:0
	ds_read_b128 v[144:147], v198 offset:2048
	ds_read_b128 v[148:151], v198 offset:4096
	ds_read_b128 v[152:155], v198 offset:6144
	ds_read_b128 v[156:159], v202
	ds_read_b128 v[216:219], v199 offset:0
	ds_read_b128 v[220:223], v199 offset:2048
	ds_read_b128 v[224:227], v199 offset:4096
	ds_read_b128 v[228:231], v199 offset:6144
	ds_read_b128 v[188:191], v203
	ds_read_b128 v[192:195], v202 offset:2048
	ds_read_b128 v[208:211], v203 offset:2048
	s_add_i32 m0, s41, 0x0
	s_nop 0
	global_load_lds_dwordx4 v200, s[50:51]
	s_add_i32 m0, s41, 0x400
	s_add_u32 s52, s50, 0x4000
	s_addc_u32 s53, s51, 0
	global_load_lds_dwordx4 v201, s[52:53]
	s_add_i32 m0, s41, 0x800
	s_add_u32 s52, s50, 0x8000
	s_addc_u32 s53, s51, 0
	global_load_lds_dwordx4 v200, s[52:53]
	s_add_i32 m0, s41, 0xc00
	s_add_u32 s52, s50, 0xc000
	s_addc_u32 s53, s51, 0
	global_load_lds_dwordx4 v201, s[52:53]
	s_waitcnt lgkmcnt(7)
	v_mfma_f32_16x16x32_bf16 v[124:127], v[140:143], v[156:159], v[124:127]
	v_mfma_f32_16x16x32_bf16 v[120:123], v[144:147], v[156:159], v[120:123]
	v_mfma_f32_16x16x32_bf16 v[116:119], v[148:151], v[156:159], v[116:119]
	v_mfma_f32_16x16x32_bf16 v[112:115], v[152:155], v[156:159], v[112:115]
	ds_read_b128 v[156:159], v202 offset:4096
	s_waitcnt lgkmcnt(3)
	v_mfma_f32_16x16x32_bf16 v[124:127], v[216:219], v[188:191], v[124:127]
	v_mfma_f32_16x16x32_bf16 v[120:123], v[220:223], v[188:191], v[120:123]
	v_mfma_f32_16x16x32_bf16 v[116:119], v[224:227], v[188:191], v[116:119]
	v_mfma_f32_16x16x32_bf16 v[112:115], v[228:231], v[188:191], v[112:115]
	ds_read_b128 v[188:191], v203 offset:4096
	s_waitcnt lgkmcnt(3)
	v_mfma_f32_16x16x32_bf16 v[108:111], v[140:143], v[192:195], v[108:111]
	v_mfma_f32_16x16x32_bf16 v[104:107], v[144:147], v[192:195], v[104:107]
	v_mfma_f32_16x16x32_bf16 v[100:103], v[148:151], v[192:195], v[100:103]
	v_mfma_f32_16x16x32_bf16 v[96:99], v[152:155], v[192:195], v[96:99]
	ds_read_b128 v[192:195], v202 offset:6144
	s_waitcnt lgkmcnt(3)
	v_mfma_f32_16x16x32_bf16 v[108:111], v[216:219], v[208:211], v[108:111]
	v_mfma_f32_16x16x32_bf16 v[104:107], v[220:223], v[208:211], v[104:107]
	v_mfma_f32_16x16x32_bf16 v[100:103], v[224:227], v[208:211], v[100:103]
	v_mfma_f32_16x16x32_bf16 v[96:99], v[228:231], v[208:211], v[96:99]
	ds_read_b128 v[208:211], v203 offset:6144
	s_waitcnt lgkmcnt(3)
	v_mfma_f32_16x16x32_bf16 v[84:87], v[140:143], v[156:159], v[84:87]
	v_mfma_f32_16x16x32_bf16 v[72:75], v[144:147], v[156:159], v[72:75]
	v_mfma_f32_16x16x32_bf16 v[68:71], v[148:151], v[156:159], v[68:71]
	v_mfma_f32_16x16x32_bf16 v[64:67], v[152:155], v[156:159], v[64:67]
	s_waitcnt lgkmcnt(2)
	v_mfma_f32_16x16x32_bf16 v[84:87], v[216:219], v[188:191], v[84:87]
	v_mfma_f32_16x16x32_bf16 v[72:75], v[220:223], v[188:191], v[72:75]
	v_mfma_f32_16x16x32_bf16 v[68:71], v[224:227], v[188:191], v[68:71]
	v_mfma_f32_16x16x32_bf16 v[64:67], v[228:231], v[188:191], v[64:67]
	s_waitcnt lgkmcnt(1)
	v_mfma_f32_16x16x32_bf16 v[60:63], v[140:143], v[192:195], v[60:63]
	v_mfma_f32_16x16x32_bf16 v[56:59], v[144:147], v[192:195], v[56:59]
	v_mfma_f32_16x16x32_bf16 v[52:55], v[148:151], v[192:195], v[52:55]
	v_mfma_f32_16x16x32_bf16 v[48:51], v[152:155], v[192:195], v[48:51]
	s_waitcnt lgkmcnt(0)
	v_mfma_f32_16x16x32_bf16 v[60:63], v[216:219], v[208:211], v[60:63]
	v_mfma_f32_16x16x32_bf16 v[56:59], v[220:223], v[208:211], v[56:59]
	v_mfma_f32_16x16x32_bf16 v[52:55], v[224:227], v[208:211], v[52:55]
	v_mfma_f32_16x16x32_bf16 v[48:51], v[228:231], v[208:211], v[48:51]
	s_add_i32 s42, s13, 1
	s_cmp_lg_u32 s13, 2
	s_cselect_b32 s13, s42, 0
	s_mul_i32 s15, s13, 0x4000
	s_add_i32 s15, s15, 16
	s_add_i32 s41, s13, 2
	s_cmp_ge_u32 s41, 3
	s_cselect_b32 s42, 3, 0
	s_sub_i32 s41, s41, s42
	s_mul_i32 s41, s41, 0x4000
	s_add_i32 s41, s41, 16
	s_add_i32 s41, s41, s54
	s_add_u32 s50, s18, s32
	s_addc_u32 s51, s19, 0
	s_add_u32 s50, s50, 0x20000
	s_addc_u32 s51, s51, 0
	s_add_u32 s46, s28, s32
	s_addc_u32 s47, s29, 0
	s_waitcnt vmcnt(4)
	s_barrier
	v_add_u32_e32 v202, s15, v196
	v_add_u32_e32 v203, s15, v197
	ds_read_b128 v[156:159], v202
	ds_read_b128 v[188:191], v203
	ds_read_b128 v[192:195], v202 offset:2048
	ds_read_b128 v[208:211], v203 offset:2048
	s_add_i32 m0, s54, 0xc010
	s_nop 0
	global_load_lds_dwordx4 v200, s[46:47]
	s_add_i32 m0, s54, 0xc410
	s_add_u32 s52, s46, 0x4000
	s_addc_u32 s53, s47, 0
	global_load_lds_dwordx4 v201, s[52:53]
	s_add_i32 m0, s54, 0xc810
	s_add_u32 s52, s46, 0x8000
	s_addc_u32 s53, s47, 0
	global_load_lds_dwordx4 v200, s[52:53]
	s_add_i32 m0, s54, 0xcc10
	s_add_u32 s52, s46, 0xc000
	s_addc_u32 s53, s47, 0
	global_load_lds_dwordx4 v201, s[52:53]
	s_add_i32 m0, s41, 0x0
	s_nop 0
	global_load_lds_dwordx4 v200, s[50:51]
	s_add_i32 m0, s41, 0x400
	s_add_u32 s52, s50, 0x4000
	s_addc_u32 s53, s51, 0
	global_load_lds_dwordx4 v201, s[52:53]
	s_add_i32 m0, s41, 0x800
	s_add_u32 s52, s50, 0x8000
	s_addc_u32 s53, s51, 0
	global_load_lds_dwordx4 v200, s[52:53]
	s_add_i32 m0, s41, 0xc00
	s_add_u32 s52, s50, 0xc000
	s_addc_u32 s53, s51, 0
	global_load_lds_dwordx4 v201, s[52:53]
	s_waitcnt lgkmcnt(3)
	v_mfma_f32_16x16x32_bf16 v[44:47], v[140:143], v[156:159], v[44:47]
	v_mfma_f32_16x16x32_bf16 v[40:43], v[144:147], v[156:159], v[40:43]
	v_mfma_f32_16x16x32_bf16 v[36:39], v[148:151], v[156:159], v[36:39]
	v_mfma_f32_16x16x32_bf16 v[32:35], v[152:155], v[156:159], v[32:35]
	ds_read_b128 v[156:159], v202 offset:4096
	s_waitcnt lgkmcnt(3)
	v_mfma_f32_16x16x32_bf16 v[44:47], v[216:219], v[188:191], v[44:47]
	v_mfma_f32_16x16x32_bf16 v[40:43], v[220:223], v[188:191], v[40:43]
	v_mfma_f32_16x16x32_bf16 v[36:39], v[224:227], v[188:191], v[36:39]
	v_mfma_f32_16x16x32_bf16 v[32:35], v[228:231], v[188:191], v[32:35]
	ds_read_b128 v[188:191], v203 offset:4096
	s_waitcnt lgkmcnt(3)
	v_mfma_f32_16x16x32_bf16 v[28:31], v[140:143], v[192:195], v[28:31]
	v_mfma_f32_16x16x32_bf16 v[24:27], v[144:147], v[192:195], v[24:27]
	v_mfma_f32_16x16x32_bf16 v[20:23], v[148:151], v[192:195], v[20:23]
	v_mfma_f32_16x16x32_bf16 v[16:19], v[152:155], v[192:195], v[16:19]
	ds_read_b128 v[192:195], v202 offset:6144
	s_waitcnt lgkmcnt(3)
	v_mfma_f32_16x16x32_bf16 v[28:31], v[216:219], v[208:211], v[28:31]
	v_mfma_f32_16x16x32_bf16 v[24:27], v[220:223], v[208:211], v[24:27]
	v_mfma_f32_16x16x32_bf16 v[20:23], v[224:227], v[208:211], v[20:23]
	v_mfma_f32_16x16x32_bf16 v[16:19], v[228:231], v[208:211], v[16:19]
	ds_read_b128 v[208:211], v203 offset:6144
	s_waitcnt lgkmcnt(3)
	v_mfma_f32_16x16x32_bf16 v[12:15], v[140:143], v[156:159], v[12:15]
	v_mfma_f32_16x16x32_bf16 v[8:11], v[144:147], v[156:159], v[8:11]
	v_mfma_f32_16x16x32_bf16 v[4:7], v[148:151], v[156:159], v[4:7]
	v_mfma_f32_16x16x32_bf16 v[0:3], v[152:155], v[156:159], v[0:3]
	s_waitcnt lgkmcnt(2)
	v_mfma_f32_16x16x32_bf16 v[12:15], v[216:219], v[188:191], v[12:15]
	v_mfma_f32_16x16x32_bf16 v[8:11], v[220:223], v[188:191], v[8:11]
	v_mfma_f32_16x16x32_bf16 v[4:7], v[224:227], v[188:191], v[4:7]
	v_mfma_f32_16x16x32_bf16 v[0:3], v[228:231], v[188:191], v[0:3]
	s_waitcnt lgkmcnt(1)
	v_mfma_f32_16x16x32_bf16 v[76:79], v[140:143], v[192:195], v[76:79]
	v_mfma_f32_16x16x32_bf16 v[80:83], v[144:147], v[192:195], v[80:83]
	v_mfma_f32_16x16x32_bf16 v[88:91], v[148:151], v[192:195], v[88:91]
	v_mfma_f32_16x16x32_bf16 v[92:95], v[152:155], v[192:195], v[92:95]
	s_waitcnt lgkmcnt(0)
	v_mfma_f32_16x16x32_bf16 v[76:79], v[216:219], v[208:211], v[76:79]
	v_mfma_f32_16x16x32_bf16 v[80:83], v[220:223], v[208:211], v[80:83]
	v_mfma_f32_16x16x32_bf16 v[88:91], v[224:227], v[208:211], v[88:91]
	v_mfma_f32_16x16x32_bf16 v[92:95], v[228:231], v[208:211], v[92:95]
	s_add_i32 s42, s13, 1
	s_cmp_lg_u32 s13, 2
	s_cselect_b32 s13, s42, 0
	s_add_i32 s14, s14, 1
	s_cmp_eq_u32 s14, 16
	s_cbranch_scc0 .LBB1_56
	s_setprio 0
	s_cmpk_lt_i32 s7, 0x80
	v_readlane_b32 s10, v242, 5
	s_waitcnt vmcnt(0)
	s_cselect_b64 s[8:9], -1, 0
	v_readlane_b32 s11, v242, 6
	s_and_b64 s[8:9], s[10:11], s[8:9]
	s_mov_b64 s[42:43], -1
	s_and_b64 vcc, exec, s[8:9]
	v_cvt_pk_bf16_f32 v124, v124, v125
	v_cvt_pk_bf16_f32 v125, v126, v127
	v_cvt_pk_bf16_f32 v120, v120, v121
	v_cvt_pk_bf16_f32 v121, v122, v123
	v_cvt_pk_bf16_f32 v116, v116, v117
	v_cvt_pk_bf16_f32 v117, v118, v119
	v_cvt_pk_bf16_f32 v112, v112, v113
	v_cvt_pk_bf16_f32 v113, v114, v115
	v_cvt_pk_bf16_f32 v108, v108, v109
	v_cvt_pk_bf16_f32 v109, v110, v111
	v_cvt_pk_bf16_f32 v104, v104, v105
	v_cvt_pk_bf16_f32 v105, v106, v107
	v_cvt_pk_bf16_f32 v100, v100, v101
	v_cvt_pk_bf16_f32 v101, v102, v103
	v_cvt_pk_bf16_f32 v96, v96, v97
	v_cvt_pk_bf16_f32 v97, v98, v99
	v_cvt_pk_bf16_f32 v84, v84, v85
	v_cvt_pk_bf16_f32 v85, v86, v87
	v_cvt_pk_bf16_f32 v72, v72, v73
	v_cvt_pk_bf16_f32 v73, v74, v75
	v_cvt_pk_bf16_f32 v68, v68, v69
	v_cvt_pk_bf16_f32 v69, v70, v71
	v_cvt_pk_bf16_f32 v64, v64, v65
	v_cvt_pk_bf16_f32 v65, v66, v67
	v_cvt_pk_bf16_f32 v60, v60, v61
	v_cvt_pk_bf16_f32 v61, v62, v63
	v_cvt_pk_bf16_f32 v56, v56, v57
	v_cvt_pk_bf16_f32 v57, v58, v59
	v_cvt_pk_bf16_f32 v52, v52, v53
	v_cvt_pk_bf16_f32 v53, v54, v55
	v_cvt_pk_bf16_f32 v48, v48, v49
	v_cvt_pk_bf16_f32 v49, v50, v51
	v_cvt_pk_bf16_f32 v44, v44, v45
	v_cvt_pk_bf16_f32 v45, v46, v47
	v_cvt_pk_bf16_f32 v40, v40, v41
	v_cvt_pk_bf16_f32 v41, v42, v43
	v_cvt_pk_bf16_f32 v36, v36, v37
	v_cvt_pk_bf16_f32 v37, v38, v39
	v_cvt_pk_bf16_f32 v32, v32, v33
	v_cvt_pk_bf16_f32 v33, v34, v35
	v_cvt_pk_bf16_f32 v28, v28, v29
	v_cvt_pk_bf16_f32 v29, v30, v31
	v_cvt_pk_bf16_f32 v24, v24, v25
	v_cvt_pk_bf16_f32 v25, v26, v27
	v_cvt_pk_bf16_f32 v20, v20, v21
	v_cvt_pk_bf16_f32 v21, v22, v23
	v_cvt_pk_bf16_f32 v16, v16, v17
	v_cvt_pk_bf16_f32 v17, v18, v19
	v_cvt_pk_bf16_f32 v12, v12, v13
	v_cvt_pk_bf16_f32 v13, v14, v15
	v_cvt_pk_bf16_f32 v14, v8, v9
	v_cvt_pk_bf16_f32 v15, v10, v11
	v_cvt_pk_bf16_f32 v8, v4, v5
	v_cvt_pk_bf16_f32 v9, v6, v7
	v_cvt_pk_bf16_f32 v10, v0, v1
	v_cvt_pk_bf16_f32 v11, v2, v3
	v_cvt_pk_bf16_f32 v2, v76, v77
	v_cvt_pk_bf16_f32 v3, v78, v79
	v_cvt_pk_bf16_f32 v6, v80, v81
	v_cvt_pk_bf16_f32 v7, v82, v83
	v_cvt_pk_bf16_f32 v0, v88, v89
	v_cvt_pk_bf16_f32 v1, v90, v91
	v_cvt_pk_bf16_f32 v4, v92, v93
	v_cvt_pk_bf16_f32 v5, v94, v95
	s_waitcnt vmcnt(0)
	s_barrier
	s_cbranch_vccnz .LBB1_59
	s_load_dwordx16 s[64:79], s[0:1], 0x140
	v_or_b32_e32 v18, s4, v135
	v_add_u32_e32 v18, s6, v18
	v_lshl_or_b32 v19, v136, 2, s40
	v_or_b32_e32 v22, s5, v19
	v_ashrrev_i32_e32 v19, 31, v18
	v_lshlrev_b64 v[26:27], 12, v[18:19]
	v_ashrrev_i32_e32 v23, 31, v22
	s_waitcnt lgkmcnt(0)
	v_lshl_add_u64 v[26:27], s[76:77], 0, v[26:27]
	v_lshlrev_b64 v[22:23], 1, v[22:23]
	v_lshl_add_u64 v[26:27], v[26:27], 0, v[22:23]
	global_store_dwordx2 v[26:27], v[124:125], off
	global_store_dwordx2 v[26:27], v[120:121], off offset:32
	global_store_dwordx2 v[26:27], v[116:117], off offset:64
	global_store_dwordx2 v[26:27], v[112:113], off offset:96
	v_or_b32_e32 v26, 16, v18
	v_ashrrev_i32_e32 v27, 31, v26
	v_lshlrev_b64 v[26:27], 12, v[26:27]
	v_lshl_add_u64 v[26:27], s[76:77], 0, v[26:27]
	v_lshl_add_u64 v[26:27], v[26:27], 0, v[22:23]
	global_store_dwordx2 v[26:27], v[108:109], off
	global_store_dwordx2 v[26:27], v[104:105], off offset:32
	global_store_dwordx2 v[26:27], v[100:101], off offset:64
	global_store_dwordx2 v[26:27], v[96:97], off offset:96
	v_or_b32_e32 v26, 32, v18
	v_ashrrev_i32_e32 v27, 31, v26
	v_lshlrev_b64 v[26:27], 12, v[26:27]
	v_lshl_add_u64 v[26:27], s[76:77], 0, v[26:27]
	v_lshl_add_u64 v[26:27], v[26:27], 0, v[22:23]
	global_store_dwordx2 v[26:27], v[84:85], off
	global_store_dwordx2 v[26:27], v[72:73], off offset:32
	global_store_dwordx2 v[26:27], v[68:69], off offset:64
	global_store_dwordx2 v[26:27], v[64:65], off offset:96
	v_or_b32_e32 v26, 48, v18
	v_ashrrev_i32_e32 v27, 31, v26
	v_lshlrev_b64 v[26:27], 12, v[26:27]
	v_lshl_add_u64 v[26:27], s[76:77], 0, v[26:27]
	v_lshl_add_u64 v[26:27], v[26:27], 0, v[22:23]
	global_store_dwordx2 v[26:27], v[60:61], off
	global_store_dwordx2 v[26:27], v[56:57], off offset:32
	global_store_dwordx2 v[26:27], v[52:53], off offset:64
	global_store_dwordx2 v[26:27], v[48:49], off offset:96
	v_or_b32_e32 v26, 64, v18
	v_ashrrev_i32_e32 v27, 31, v26
	v_lshlrev_b64 v[26:27], 12, v[26:27]
	v_lshl_add_u64 v[26:27], s[76:77], 0, v[26:27]
	v_lshl_add_u64 v[26:27], v[26:27], 0, v[22:23]
	global_store_dwordx2 v[26:27], v[44:45], off
	global_store_dwordx2 v[26:27], v[40:41], off offset:32
	global_store_dwordx2 v[26:27], v[36:37], off offset:64
	global_store_dwordx2 v[26:27], v[32:33], off offset:96
	v_or_b32_e32 v26, 0x50, v18
	v_ashrrev_i32_e32 v27, 31, v26
	v_lshlrev_b64 v[26:27], 12, v[26:27]
	v_lshl_add_u64 v[26:27], s[76:77], 0, v[26:27]
	v_lshl_add_u64 v[26:27], v[26:27], 0, v[22:23]
	global_store_dwordx2 v[26:27], v[28:29], off
	global_store_dwordx2 v[26:27], v[24:25], off offset:32
	global_store_dwordx2 v[26:27], v[20:21], off offset:64
	global_store_dwordx2 v[26:27], v[16:17], off offset:96
	v_or_b32_e32 v26, 0x60, v18
	v_ashrrev_i32_e32 v27, 31, v26
	v_lshlrev_b64 v[26:27], 12, v[26:27]
	v_lshl_add_u64 v[26:27], s[76:77], 0, v[26:27]
	v_or_b32_e32 v18, 0x70, v18
	v_lshl_add_u64 v[26:27], v[26:27], 0, v[22:23]
	v_ashrrev_i32_e32 v19, 31, v18
	global_store_dwordx2 v[26:27], v[12:13], off
	global_store_dwordx2 v[26:27], v[14:15], off offset:32
	global_store_dwordx2 v[26:27], v[8:9], off offset:64
	global_store_dwordx2 v[26:27], v[10:11], off offset:96
	v_lshlrev_b64 v[18:19], 12, v[18:19]
	v_lshl_add_u64 v[18:19], s[76:77], 0, v[18:19]
	s_load_dwordx16 s[64:79], s[0:1], 0x100
	v_lshl_add_u64 v[18:19], v[18:19], 0, v[22:23]
	s_mov_b64 s[42:43], 0
	global_store_dwordx2 v[18:19], v[2:3], off
	global_store_dwordx2 v[18:19], v[6:7], off offset:32
	global_store_dwordx2 v[18:19], v[0:1], off offset:64
	global_store_dwordx2 v[18:19], v[4:5], off offset:96

.LBB1_1180:
	s_mul_i32 s15, s13, 0x4000
	s_add_i32 s15, s15, 16
	s_add_i32 s41, s13, 2
	s_cmp_ge_u32 s41, 3
	s_cselect_b32 s42, 3, 0
	s_sub_i32 s41, s41, s42
	s_mul_i32 s41, s41, 0x4000
	s_add_i32 s41, s41, 16
	s_add_i32 s41, s41, s54
	s_add_i32 s32, s14, 1
	s_min_u32 s32, s32, 15
	s_lshl_b32 s32, s32, 7
	s_add_u32 s50, s18, s32
	s_addc_u32 s51, s19, 0
	s_waitcnt vmcnt(4)
	s_barrier
	v_add_u32_e32 v202, s15, v196
	v_add_u32_e32 v203, s15, v197
	ds_read_b128 v[142:145], v198 offset:0
	ds_read_b128 v[146:149], v198 offset:2048
	ds_read_b128 v[150:153], v198 offset:4096
	ds_read_b128 v[154:157], v198 offset:6144
	ds_read_b128 v[158:161], v202
	ds_read_b128 v[216:219], v199 offset:0
	ds_read_b128 v[220:223], v199 offset:2048
	ds_read_b128 v[224:227], v199 offset:4096
	ds_read_b128 v[228:231], v199 offset:6144
	ds_read_b128 v[188:191], v203
	ds_read_b128 v[192:195], v202 offset:2048
	ds_read_b128 v[208:211], v203 offset:2048
	s_add_i32 m0, s41, 0x0
	s_nop 0
	global_load_lds_dwordx4 v200, s[50:51]
	s_add_i32 m0, s41, 0x400
	s_add_u32 s52, s50, 0x4000
	s_addc_u32 s53, s51, 0
	global_load_lds_dwordx4 v201, s[52:53]
	s_add_i32 m0, s41, 0x800
	s_add_u32 s52, s50, 0x8000
	s_addc_u32 s53, s51, 0
	global_load_lds_dwordx4 v200, s[52:53]
	s_add_i32 m0, s41, 0xc00
	s_add_u32 s52, s50, 0xc000
	s_addc_u32 s53, s51, 0
	global_load_lds_dwordx4 v201, s[52:53]
	s_waitcnt lgkmcnt(7)
	v_mfma_f32_16x16x32_bf16 v[124:127], v[142:145], v[158:161], v[124:127]
	v_mfma_f32_16x16x32_bf16 v[120:123], v[146:149], v[158:161], v[120:123]
	v_mfma_f32_16x16x32_bf16 v[116:119], v[150:153], v[158:161], v[116:119]
	v_mfma_f32_16x16x32_bf16 v[112:115], v[154:157], v[158:161], v[112:115]
	ds_read_b128 v[158:161], v202 offset:4096
	s_waitcnt lgkmcnt(3)
	v_mfma_f32_16x16x32_bf16 v[124:127], v[216:219], v[188:191], v[124:127]
	v_mfma_f32_16x16x32_bf16 v[120:123], v[220:223], v[188:191], v[120:123]
	v_mfma_f32_16x16x32_bf16 v[116:119], v[224:227], v[188:191], v[116:119]
	v_mfma_f32_16x16x32_bf16 v[112:115], v[228:231], v[188:191], v[112:115]
	ds_read_b128 v[188:191], v203 offset:4096
	s_waitcnt lgkmcnt(3)
	v_mfma_f32_16x16x32_bf16 v[108:111], v[142:145], v[192:195], v[108:111]
	v_mfma_f32_16x16x32_bf16 v[104:107], v[146:149], v[192:195], v[104:107]
	v_mfma_f32_16x16x32_bf16 v[100:103], v[150:153], v[192:195], v[100:103]
	v_mfma_f32_16x16x32_bf16 v[96:99], v[154:157], v[192:195], v[96:99]
	ds_read_b128 v[192:195], v202 offset:6144
	s_waitcnt lgkmcnt(3)
	v_mfma_f32_16x16x32_bf16 v[108:111], v[216:219], v[208:211], v[108:111]
	v_mfma_f32_16x16x32_bf16 v[104:107], v[220:223], v[208:211], v[104:107]
	v_mfma_f32_16x16x32_bf16 v[100:103], v[224:227], v[208:211], v[100:103]
	v_mfma_f32_16x16x32_bf16 v[96:99], v[228:231], v[208:211], v[96:99]
	ds_read_b128 v[208:211], v203 offset:6144
	s_waitcnt lgkmcnt(3)
	v_mfma_f32_16x16x32_bf16 v[92:95], v[142:145], v[158:161], v[92:95]
	v_mfma_f32_16x16x32_bf16 v[88:91], v[146:149], v[158:161], v[88:91]
	v_mfma_f32_16x16x32_bf16 v[84:87], v[150:153], v[158:161], v[84:87]
	v_mfma_f32_16x16x32_bf16 v[80:83], v[154:157], v[158:161], v[80:83]
	s_waitcnt lgkmcnt(2)
	v_mfma_f32_16x16x32_bf16 v[92:95], v[216:219], v[188:191], v[92:95]
	v_mfma_f32_16x16x32_bf16 v[88:91], v[220:223], v[188:191], v[88:91]
	v_mfma_f32_16x16x32_bf16 v[84:87], v[224:227], v[188:191], v[84:87]
	v_mfma_f32_16x16x32_bf16 v[80:83], v[228:231], v[188:191], v[80:83]
	s_waitcnt lgkmcnt(1)
	v_mfma_f32_16x16x32_bf16 v[76:79], v[142:145], v[192:195], v[76:79]
	v_mfma_f32_16x16x32_bf16 v[72:75], v[146:149], v[192:195], v[72:75]
	v_mfma_f32_16x16x32_bf16 v[68:71], v[150:153], v[192:195], v[68:71]
	v_mfma_f32_16x16x32_bf16 v[48:51], v[154:157], v[192:195], v[48:51]
	s_waitcnt lgkmcnt(0)
	v_mfma_f32_16x16x32_bf16 v[76:79], v[216:219], v[208:211], v[76:79]
	v_mfma_f32_16x16x32_bf16 v[72:75], v[220:223], v[208:211], v[72:75]
	v_mfma_f32_16x16x32_bf16 v[68:71], v[224:227], v[208:211], v[68:71]
	v_mfma_f32_16x16x32_bf16 v[48:51], v[228:231], v[208:211], v[48:51]
	s_add_i32 s42, s13, 1
	s_cmp_lg_u32 s13, 2
	s_cselect_b32 s13, s42, 0
	s_mul_i32 s15, s13, 0x4000
	s_add_i32 s15, s15, 16
	s_add_i32 s41, s13, 2
	s_cmp_ge_u32 s41, 3
	s_cselect_b32 s42, 3, 0
	s_sub_i32 s41, s41, s42
	s_mul_i32 s41, s41, 0x4000
	s_add_i32 s41, s41, 16
	s_add_i32 s41, s41, s54
	s_add_u32 s50, s18, s32
	s_addc_u32 s51, s19, 0
	s_add_u32 s50, s50, 0x20000
	s_addc_u32 s51, s51, 0
	s_add_u32 s46, s28, s32
	s_addc_u32 s47, s29, 0
	s_waitcnt vmcnt(4)
	s_barrier
	v_add_u32_e32 v202, s15, v196
	v_add_u32_e32 v203, s15, v197
	ds_read_b128 v[158:161], v202
	ds_read_b128 v[188:191], v203
	ds_read_b128 v[192:195], v202 offset:2048
	ds_read_b128 v[208:211], v203 offset:2048
	s_add_i32 m0, s54, 0xc010
	s_nop 0
	global_load_lds_dwordx4 v200, s[46:47]
	s_add_i32 m0, s54, 0xc410
	s_add_u32 s52, s46, 0x4000
	s_addc_u32 s53, s47, 0
	global_load_lds_dwordx4 v201, s[52:53]
	s_add_i32 m0, s54, 0xc810
	s_add_u32 s52, s46, 0x8000
	s_addc_u32 s53, s47, 0
	global_load_lds_dwordx4 v200, s[52:53]
	s_add_i32 m0, s54, 0xcc10
	s_add_u32 s52, s46, 0xc000
	s_addc_u32 s53, s47, 0
	global_load_lds_dwordx4 v201, s[52:53]
	s_add_i32 m0, s41, 0x0
	s_nop 0
	global_load_lds_dwordx4 v200, s[50:51]
	s_add_i32 m0, s41, 0x400
	s_add_u32 s52, s50, 0x4000
	s_addc_u32 s53, s51, 0
	global_load_lds_dwordx4 v201, s[52:53]
	s_add_i32 m0, s41, 0x800
	s_add_u32 s52, s50, 0x8000
	s_addc_u32 s53, s51, 0
	global_load_lds_dwordx4 v200, s[52:53]
	s_add_i32 m0, s41, 0xc00
	s_add_u32 s52, s50, 0xc000
	s_addc_u32 s53, s51, 0
	global_load_lds_dwordx4 v201, s[52:53]
	s_waitcnt lgkmcnt(3)
	v_mfma_f32_16x16x32_bf16 v[44:47], v[142:145], v[158:161], v[44:47]
	v_mfma_f32_16x16x32_bf16 v[40:43], v[146:149], v[158:161], v[40:43]
	v_mfma_f32_16x16x32_bf16 v[36:39], v[150:153], v[158:161], v[36:39]
	v_mfma_f32_16x16x32_bf16 v[32:35], v[154:157], v[158:161], v[32:35]
	ds_read_b128 v[158:161], v202 offset:4096
	s_waitcnt lgkmcnt(3)
	v_mfma_f32_16x16x32_bf16 v[44:47], v[216:219], v[188:191], v[44:47]
	v_mfma_f32_16x16x32_bf16 v[40:43], v[220:223], v[188:191], v[40:43]
	v_mfma_f32_16x16x32_bf16 v[36:39], v[224:227], v[188:191], v[36:39]
	v_mfma_f32_16x16x32_bf16 v[32:35], v[228:231], v[188:191], v[32:35]
	ds_read_b128 v[188:191], v203 offset:4096
	s_waitcnt lgkmcnt(3)
	v_mfma_f32_16x16x32_bf16 v[28:31], v[142:145], v[192:195], v[28:31]
	v_mfma_f32_16x16x32_bf16 v[24:27], v[146:149], v[192:195], v[24:27]
	v_mfma_f32_16x16x32_bf16 v[20:23], v[150:153], v[192:195], v[20:23]
	v_mfma_f32_16x16x32_bf16 v[16:19], v[154:157], v[192:195], v[16:19]
	ds_read_b128 v[192:195], v202 offset:6144
	s_waitcnt lgkmcnt(3)
	v_mfma_f32_16x16x32_bf16 v[28:31], v[216:219], v[208:211], v[28:31]
	v_mfma_f32_16x16x32_bf16 v[24:27], v[220:223], v[208:211], v[24:27]
	v_mfma_f32_16x16x32_bf16 v[20:23], v[224:227], v[208:211], v[20:23]
	v_mfma_f32_16x16x32_bf16 v[16:19], v[228:231], v[208:211], v[16:19]
	ds_read_b128 v[208:211], v203 offset:6144
	s_waitcnt lgkmcnt(3)
	v_mfma_f32_16x16x32_bf16 v[12:15], v[142:145], v[158:161], v[12:15]
	v_mfma_f32_16x16x32_bf16 v[8:11], v[146:149], v[158:161], v[8:11]
	v_mfma_f32_16x16x32_bf16 v[4:7], v[150:153], v[158:161], v[4:7]
	v_mfma_f32_16x16x32_bf16 v[0:3], v[154:157], v[158:161], v[0:3]
	s_waitcnt lgkmcnt(2)
	v_mfma_f32_16x16x32_bf16 v[12:15], v[216:219], v[188:191], v[12:15]
	v_mfma_f32_16x16x32_bf16 v[8:11], v[220:223], v[188:191], v[8:11]
	v_mfma_f32_16x16x32_bf16 v[4:7], v[224:227], v[188:191], v[4:7]
	v_mfma_f32_16x16x32_bf16 v[0:3], v[228:231], v[188:191], v[0:3]
	s_waitcnt lgkmcnt(1)
	v_mfma_f32_16x16x32_bf16 v[60:63], v[142:145], v[192:195], v[60:63]
	v_mfma_f32_16x16x32_bf16 v[64:67], v[146:149], v[192:195], v[64:67]
	v_mfma_f32_16x16x32_bf16 v[52:55], v[150:153], v[192:195], v[52:55]
	v_mfma_f32_16x16x32_bf16 v[56:59], v[154:157], v[192:195], v[56:59]
	s_waitcnt lgkmcnt(0)
	v_mfma_f32_16x16x32_bf16 v[60:63], v[216:219], v[208:211], v[60:63]
	v_mfma_f32_16x16x32_bf16 v[64:67], v[220:223], v[208:211], v[64:67]
	v_mfma_f32_16x16x32_bf16 v[52:55], v[224:227], v[208:211], v[52:55]
	v_mfma_f32_16x16x32_bf16 v[56:59], v[228:231], v[208:211], v[56:59]
	s_add_i32 s42, s13, 1
	s_cmp_lg_u32 s13, 2
	s_cselect_b32 s13, s42, 0
	s_add_i32 s14, s14, 1
	s_cmp_eq_u32 s14, 16
	s_cbranch_scc0 .LBB1_1180
	s_setprio 0
	s_waitcnt vmcnt(0)
	s_waitcnt vmcnt(0)
	s_barrier
	s_load_dwordx8 s[80:87], s[0:1], 0x180
	s_cmp_lt_i32 s4, 64
	v_readlane_b32 s12, v242, 9
	s_cselect_b64 s[10:11], -1, 0
	v_readlane_b32 s13, v242, 10
	s_and_b64 s[10:11], s[12:13], s[10:11]
	s_mov_b64 s[38:39], -1
	s_and_b64 vcc, exec, s[10:11]
	s_movk_i32 s12, 0x2020
	s_cbranch_vccnz .LBB1_1291
	v_or_b32_e32 v128, s6, v139
	v_add_u32_e32 v132, s8, v128
	v_lshl_or_b32 v128, v140, 2, s30
	v_or_b32_e32 v130, s7, v128
	v_lshlrev_b32_e32 v134, 5, v132
	s_movk_i32 s8, 0x1fff
	v_ashrrev_i32_e32 v135, 31, v134
	v_cmp_lt_i32_e32 vcc, s8, v130
	s_and_saveexec_b64 s[8:9], vcc
	s_xor_b64 s[40:41], exec, s[8:9]
	s_cbranch_execz .LBB1_1186
	v_cmp_gt_u32_e64 s[38:39], s12, v130
	s_and_saveexec_b64 s[42:43], s[38:39]
	s_cbranch_execz .LBB1_1185
	v_add_u32_e32 v128, 0xffffe000, v130
	v_lshl_add_u64 v[136:137], v[134:135], 2, s[78:79]
	v_lshlrev_b64 v[142:143], 2, v[128:129]
	v_lshl_add_u64 v[136:137], v[136:137], 0, v[142:143]
	v_lshl_add_u64 v[142:143], s[22:23], 0, v[142:143]
	global_load_dwordx4 v[142:145], v[142:143], off
	s_waitcnt vmcnt(0)
	v_pk_add_f32 v[144:145], v[126:127], v[144:145]
	v_pk_add_f32 v[142:143], v[124:125], v[142:143]
	global_store_dwordx4 v[136:137], v[142:145], off
